# no grid barrier after the final phase (workgroups end after phase 12)
# speedup vs baseline: 1.0797x; 1.0092x over previous
.LBB0_539:
	s_cmp_eq_u32 s42, 12
	s_cbranch_scc1 .LBB0_600
	s_and_saveexec_b64 s[0:1], s[96:97]
	s_cbranch_execz .LBB0_551
	v_readlane_b32 s2, v254, 36
	v_readlane_b32 s3, v254, 37
	s_waitcnt lgkmcnt(0)
	s_barrier
	s_and_b64 exec, exec, s[2:3]
	s_cbranch_execz .LBB0_550
	buffer_wbl2 sc1
	s_waitcnt vmcnt(0)
	s_load_dwordx2 s[2:3], s[60:61], 0x58
	s_mov_b64 s[4:5], exec
	v_mbcnt_lo_u32_b32 v1, s4, 0
	v_mbcnt_hi_u32_b32 v1, s5, v1
	v_cmp_eq_u32_e32 vcc, 0, v1
	s_waitcnt lgkmcnt(0)
	global_load_dword v0, v187, s[2:3] offset:40
	s_and_saveexec_b64 s[6:7], vcc
	s_cbranch_execz .LBB0_543
	s_bcnt1_i32_b64 s4, s[4:5]
	v_mov_b32_e32 v2, s4
	global_atomic_add v2, v187, v2, s[2:3] offset:32 sc0
